# grid barriers: waiters poll the top-level arrival counter (count >> 3 == generation) instead of the generation word published one round trip later
# speedup vs baseline: 1.0103x; 1.0018x over previous
.LBB0_72:
	s_or_b64 exec, exec, s[36:37]
	v_cvt_f32_u32_e32 v4, v2
	s_waitcnt vmcnt(1)
	v_readfirstlane_b32 s22, v3
	v_sub_u32_e32 v3, 0, v2
	v_rcp_iflag_f32_e32 v4, v4
	v_add_u32_e32 v5, s22, v1
	v_mul_f32_e32 v4, 0x4f7ffffe, v4
	v_cvt_u32_f32_e32 v4, v4
	v_mul_lo_u32 v1, v3, v4
	v_mul_hi_u32 v1, v4, v1
	v_add_u32_e32 v1, v4, v1
	v_mul_hi_u32 v1, v5, v1
	v_mul_lo_u32 v3, v1, v2
	v_sub_u32_e32 v3, v5, v3
	v_add_u32_e32 v4, 1, v1
	v_cmp_ge_u32_e32 vcc, v3, v2
	s_nop 1
	v_cndmask_b32_e32 v1, v1, v4, vcc
	v_sub_u32_e32 v4, v3, v2
	v_cndmask_b32_e32 v3, v3, v4, vcc
	v_add_u32_e32 v4, 1, v1
	v_cmp_ge_u32_e32 vcc, v3, v2
	v_add_u32_e32 v3, 1, v5
	s_nop 0
	v_cndmask_b32_e32 v1, v1, v4, vcc
	v_mul_lo_u32 v4, v2, v1
	v_add_u32_e32 v2, v4, v2
	v_cmp_ne_u32_e32 vcc, v3, v2
	s_and_saveexec_b64 s[22:23], vcc
	s_xor_b64 s[36:37], exec, s[22:23]
	s_cbranch_execz .LBB0_86
	s_waitcnt lgkmcnt(0)
	v_mov_b32_e32 v0, 0
	global_load_dword v2, v0, s[34:35] sc1
	s_waitcnt vmcnt(0)
	v_lshrrev_b32_e32 v2, 3, v2
	v_cmp_eq_u32_e32 vcc, v2, v1
	s_and_saveexec_b64 s[38:39], vcc
	s_cbranch_execz .LBB0_85
	s_mov_b32 s22, 1
	s_mov_b64 s[40:41], 0
	s_branch .LBB0_76

.LBB0_80:
	global_load_dword v2, v0, s[34:35] sc1
	s_add_i32 s22, s22, 1
	s_mov_b64 s[46:47], -1
	s_waitcnt vmcnt(0)
	v_lshrrev_b32_e32 v2, 3, v2
	v_cmp_ne_u32_e32 vcc, v2, v1
	s_orn2_b64 s[44:45], vcc, exec
	s_branch .LBB0_75

.LBB0_89:
	s_or_b64 exec, exec, s[38:39]
	v_cvt_f32_u32_e32 v3, v0
	s_waitcnt vmcnt(0)
	v_readfirstlane_b32 s22, v2
	s_mov_b64 s[38:39], -1
	v_rcp_iflag_f32_e32 v3, v3
	v_add_u32_e32 v1, s22, v1
	v_add_u32_e32 v4, 1, v1
	v_mul_f32_e32 v2, 0x4f7ffffe, v3
	v_cvt_u32_f32_e32 v2, v2
	v_sub_u32_e32 v3, 0, v0
	v_mul_lo_u32 v3, v3, v2
	v_mul_hi_u32 v3, v2, v3
	v_add_u32_e32 v2, v2, v3
	v_mul_hi_u32 v2, v1, v2
	v_mul_lo_u32 v3, v2, v0
	v_sub_u32_e32 v1, v1, v3
	v_add_u32_e32 v5, 1, v2
	v_cmp_ge_u32_e32 vcc, v1, v0
	v_sub_u32_e32 v3, v1, v0
	s_nop 0
	v_cndmask_b32_e32 v2, v2, v5, vcc
	v_cndmask_b32_e32 v1, v1, v3, vcc
	v_add_u32_e32 v3, 1, v2
	v_cmp_ge_u32_e32 vcc, v1, v0
	s_nop 1
	v_cndmask_b32_e32 v2, v2, v3, vcc
	v_mul_lo_u32 v1, v0, v2
	v_add_u32_e32 v0, v1, v0
	v_cmp_ne_u32_e32 vcc, v4, v0
	v_mov_b64_e32 v[0:1], s[14:15]
	s_and_saveexec_b64 s[36:37], vcc
	s_cbranch_execz .LBB0_101
	v_mov_b32_e32 v0, 0
	global_load_dword v1, v0, s[34:35] sc1
	s_mov_b64 s[40:41], 0
	s_waitcnt vmcnt(0)
	v_lshrrev_b32_e32 v1, 3, v1
	v_cmp_eq_u32_e32 vcc, v1, v2
	s_and_saveexec_b64 s[38:39], vcc
	s_cbranch_execz .LBB0_100
	s_mov_b32 s22, 1
	s_branch .LBB0_93

.LBB0_97:
	global_load_dword v1, v0, s[34:35] sc1
	s_add_i32 s22, s22, 1
	s_mov_b64 s[44:45], -1
	s_waitcnt vmcnt(0)
	v_lshrrev_b32_e32 v1, 3, v1
	v_cmp_ne_u32_e32 vcc, v1, v2
	s_orn2_b64 s[48:49], vcc, exec
	s_branch .LBB0_92

.LBB0_1082:
	s_or_b64 exec, exec, s[12:13]
	v_cvt_f32_u32_e32 v4, v2
	s_waitcnt vmcnt(1)
	v_readfirstlane_b32 s12, v3
	v_sub_u32_e32 v3, 0, v2
	v_rcp_iflag_f32_e32 v4, v4
	v_add_u32_e32 v5, s12, v1
	v_mul_f32_e32 v4, 0x4f7ffffe, v4
	v_cvt_u32_f32_e32 v4, v4
	v_mul_lo_u32 v1, v3, v4
	v_mul_hi_u32 v1, v4, v1
	v_add_u32_e32 v1, v4, v1
	v_mul_hi_u32 v1, v5, v1
	v_mul_lo_u32 v3, v1, v2
	v_sub_u32_e32 v3, v5, v3
	v_add_u32_e32 v4, 1, v1
	v_cmp_ge_u32_e32 vcc, v3, v2
	s_nop 1
	v_cndmask_b32_e32 v1, v1, v4, vcc
	v_sub_u32_e32 v4, v3, v2
	v_cndmask_b32_e32 v3, v3, v4, vcc
	v_add_u32_e32 v4, 1, v1
	v_cmp_ge_u32_e32 vcc, v3, v2
	v_add_u32_e32 v3, 1, v5
	s_nop 0
	v_cndmask_b32_e32 v1, v1, v4, vcc
	v_mul_lo_u32 v4, v2, v1
	v_add_u32_e32 v2, v4, v2
	v_cmp_ne_u32_e32 vcc, v3, v2
	s_and_saveexec_b64 s[12:13], vcc
	s_xor_b64 s[12:13], exec, s[12:13]
	s_cbranch_execz .LBB0_1096
	s_waitcnt lgkmcnt(0)
	v_mov_b32_e32 v0, 0
	global_load_dword v2, v0, s[34:35] sc1
	s_waitcnt vmcnt(0)
	v_lshrrev_b32_e32 v2, 3, v2
	v_cmp_eq_u32_e32 vcc, v2, v1
	s_and_saveexec_b64 s[16:17], vcc
	s_cbranch_execz .LBB0_1095
	s_mov_b32 s22, 1
	s_mov_b64 s[18:19], 0
	s_branch .LBB0_1086

.LBB0_1090:
	global_load_dword v2, v0, s[34:35] sc1
	s_add_i32 s22, s22, 1
	s_mov_b64 s[40:41], -1
	s_waitcnt vmcnt(0)
	v_lshrrev_b32_e32 v2, 3, v2
	v_cmp_ne_u32_e32 vcc, v2, v1
	s_orn2_b64 s[38:39], vcc, exec
	s_branch .LBB0_1085

.LBB0_1099:
	s_or_b64 exec, exec, s[16:17]
	v_cvt_f32_u32_e32 v3, v0
	s_waitcnt vmcnt(0)
	v_readfirstlane_b32 s12, v2
	s_mov_b64 s[16:17], -1
	v_rcp_iflag_f32_e32 v3, v3
	v_add_u32_e32 v1, s12, v1
	v_add_u32_e32 v4, 1, v1
	v_mul_f32_e32 v2, 0x4f7ffffe, v3
	v_cvt_u32_f32_e32 v2, v2
	v_sub_u32_e32 v3, 0, v0
	v_mul_lo_u32 v3, v3, v2
	v_mul_hi_u32 v3, v2, v3
	v_add_u32_e32 v2, v2, v3
	v_mul_hi_u32 v2, v1, v2
	v_mul_lo_u32 v3, v2, v0
	v_sub_u32_e32 v1, v1, v3
	v_add_u32_e32 v5, 1, v2
	v_cmp_ge_u32_e32 vcc, v1, v0
	v_sub_u32_e32 v3, v1, v0
	s_nop 0
	v_cndmask_b32_e32 v2, v2, v5, vcc
	v_cndmask_b32_e32 v1, v1, v3, vcc
	v_add_u32_e32 v3, 1, v2
	v_cmp_ge_u32_e32 vcc, v1, v0
	s_nop 1
	v_cndmask_b32_e32 v2, v2, v3, vcc
	v_mul_lo_u32 v1, v0, v2
	v_add_u32_e32 v0, v1, v0
	v_cmp_ne_u32_e32 vcc, v4, v0
	v_mov_b64_e32 v[0:1], s[14:15]
	s_and_saveexec_b64 s[12:13], vcc
	s_cbranch_execz .LBB0_1111
	v_mov_b32_e32 v0, 0
	global_load_dword v1, v0, s[34:35] sc1
	s_mov_b64 s[18:19], 0
	s_waitcnt vmcnt(0)
	v_lshrrev_b32_e32 v1, 3, v1
	v_cmp_eq_u32_e32 vcc, v1, v2
	s_and_saveexec_b64 s[16:17], vcc
	s_cbranch_execz .LBB0_1110
	s_mov_b32 s22, 1
	s_branch .LBB0_1103

.LBB0_1107:
	global_load_dword v1, v0, s[34:35] sc1
	s_add_i32 s22, s22, 1
	s_mov_b64 s[38:39], -1
	s_waitcnt vmcnt(0)
	v_lshrrev_b32_e32 v1, 3, v1
	v_cmp_ne_u32_e32 vcc, v1, v2
	s_orn2_b64 s[42:43], vcc, exec
	s_branch .LBB0_1102

.LBB0_1187:
	s_or_b64 exec, exec, s[12:13]
	v_cvt_f32_u32_e32 v4, v2
	s_waitcnt vmcnt(1)
	v_readfirstlane_b32 s12, v3
	v_sub_u32_e32 v3, 0, v2
	v_rcp_iflag_f32_e32 v4, v4
	v_add_u32_e32 v5, s12, v1
	v_mul_f32_e32 v4, 0x4f7ffffe, v4
	v_cvt_u32_f32_e32 v4, v4
	v_mul_lo_u32 v1, v3, v4
	v_mul_hi_u32 v1, v4, v1
	v_add_u32_e32 v1, v4, v1
	v_mul_hi_u32 v1, v5, v1
	v_mul_lo_u32 v3, v1, v2
	v_sub_u32_e32 v3, v5, v3
	v_add_u32_e32 v4, 1, v1
	v_cmp_ge_u32_e32 vcc, v3, v2
	s_nop 1
	v_cndmask_b32_e32 v1, v1, v4, vcc
	v_sub_u32_e32 v4, v3, v2
	v_cndmask_b32_e32 v3, v3, v4, vcc
	v_add_u32_e32 v4, 1, v1
	v_cmp_ge_u32_e32 vcc, v3, v2
	v_add_u32_e32 v3, 1, v5
	s_nop 0
	v_cndmask_b32_e32 v1, v1, v4, vcc
	v_mul_lo_u32 v4, v2, v1
	v_add_u32_e32 v2, v4, v2
	v_cmp_ne_u32_e32 vcc, v3, v2
	s_and_saveexec_b64 s[12:13], vcc
	s_xor_b64 s[12:13], exec, s[12:13]
	s_cbranch_execz .LBB0_1201
	s_waitcnt lgkmcnt(0)
	v_mov_b32_e32 v0, 0
	global_load_dword v2, v0, s[34:35] sc1
	s_waitcnt vmcnt(0)
	v_lshrrev_b32_e32 v2, 3, v2
	v_cmp_eq_u32_e32 vcc, v2, v1
	s_and_saveexec_b64 s[16:17], vcc
	s_cbranch_execz .LBB0_1200
	s_mov_b32 s23, 1
	s_mov_b64 s[18:19], 0
	s_branch .LBB0_1191

.LBB0_1195:
	global_load_dword v2, v0, s[34:35] sc1
	s_add_i32 s23, s23, 1
	s_mov_b64 s[40:41], -1
	s_waitcnt vmcnt(0)
	v_lshrrev_b32_e32 v2, 3, v2
	v_cmp_ne_u32_e32 vcc, v2, v1
	s_orn2_b64 s[38:39], vcc, exec
	s_branch .LBB0_1190

.LBB0_1204:
	s_or_b64 exec, exec, s[16:17]
	v_cvt_f32_u32_e32 v3, v0
	s_waitcnt vmcnt(0)
	v_readfirstlane_b32 s12, v2
	s_mov_b64 s[16:17], -1
	v_rcp_iflag_f32_e32 v3, v3
	v_add_u32_e32 v1, s12, v1
	v_add_u32_e32 v4, 1, v1
	v_mul_f32_e32 v2, 0x4f7ffffe, v3
	v_cvt_u32_f32_e32 v2, v2
	v_sub_u32_e32 v3, 0, v0
	v_mul_lo_u32 v3, v3, v2
	v_mul_hi_u32 v3, v2, v3
	v_add_u32_e32 v2, v2, v3
	v_mul_hi_u32 v2, v1, v2
	v_mul_lo_u32 v3, v2, v0
	v_sub_u32_e32 v1, v1, v3
	v_add_u32_e32 v5, 1, v2
	v_cmp_ge_u32_e32 vcc, v1, v0
	v_sub_u32_e32 v3, v1, v0
	s_nop 0
	v_cndmask_b32_e32 v2, v2, v5, vcc
	v_cndmask_b32_e32 v1, v1, v3, vcc
	v_add_u32_e32 v3, 1, v2
	v_cmp_ge_u32_e32 vcc, v1, v0
	s_nop 1
	v_cndmask_b32_e32 v2, v2, v3, vcc
	v_mul_lo_u32 v1, v0, v2
	v_add_u32_e32 v0, v1, v0
	v_cmp_ne_u32_e32 vcc, v4, v0
	v_mov_b64_e32 v[0:1], s[14:15]
	s_and_saveexec_b64 s[12:13], vcc
	s_cbranch_execz .LBB0_1216
	v_mov_b32_e32 v0, 0
	global_load_dword v1, v0, s[34:35] sc1
	s_mov_b64 s[18:19], 0
	s_waitcnt vmcnt(0)
	v_lshrrev_b32_e32 v1, 3, v1
	v_cmp_eq_u32_e32 vcc, v1, v2
	s_and_saveexec_b64 s[16:17], vcc
	s_cbranch_execz .LBB0_1215
	s_mov_b32 s23, 1
	s_branch .LBB0_1208

.LBB0_1212:
	global_load_dword v1, v0, s[34:35] sc1
	s_add_i32 s23, s23, 1
	s_mov_b64 s[38:39], -1
	s_waitcnt vmcnt(0)
	v_lshrrev_b32_e32 v1, 3, v1
	v_cmp_ne_u32_e32 vcc, v1, v2
	s_orn2_b64 s[42:43], vcc, exec
	s_branch .LBB0_1207

.LBB0_1242:
	s_or_b64 exec, exec, s[16:17]
	v_cvt_f32_u32_e32 v4, v2
	s_waitcnt vmcnt(1)
	v_readfirstlane_b32 s16, v3
	v_sub_u32_e32 v3, 0, v2
	v_rcp_iflag_f32_e32 v4, v4
	v_add_u32_e32 v5, s16, v1
	v_mul_f32_e32 v4, 0x4f7ffffe, v4
	v_cvt_u32_f32_e32 v4, v4
	v_mul_lo_u32 v1, v3, v4
	v_mul_hi_u32 v1, v4, v1
	v_add_u32_e32 v1, v4, v1
	v_mul_hi_u32 v1, v5, v1
	v_mul_lo_u32 v3, v1, v2
	v_sub_u32_e32 v3, v5, v3
	v_add_u32_e32 v4, 1, v1
	v_cmp_ge_u32_e32 vcc, v3, v2
	s_nop 1
	v_cndmask_b32_e32 v1, v1, v4, vcc
	v_sub_u32_e32 v4, v3, v2
	v_cndmask_b32_e32 v3, v3, v4, vcc
	v_add_u32_e32 v4, 1, v1
	v_cmp_ge_u32_e32 vcc, v3, v2
	v_add_u32_e32 v3, 1, v5
	s_nop 0
	v_cndmask_b32_e32 v1, v1, v4, vcc
	v_mul_lo_u32 v4, v2, v1
	v_add_u32_e32 v2, v4, v2
	v_cmp_ne_u32_e32 vcc, v3, v2
	s_and_saveexec_b64 s[16:17], vcc
	s_xor_b64 s[16:17], exec, s[16:17]
	s_cbranch_execz .LBB0_1256
	s_waitcnt lgkmcnt(0)
	v_mov_b32_e32 v0, 0
	global_load_dword v2, v0, s[34:35] sc1
	s_waitcnt vmcnt(0)
	v_lshrrev_b32_e32 v2, 3, v2
	v_cmp_eq_u32_e32 vcc, v2, v1
	s_and_saveexec_b64 s[18:19], vcc
	s_cbranch_execz .LBB0_1255
	s_mov_b32 s22, 1
	s_mov_b64 s[36:37], 0
	s_branch .LBB0_1246

.LBB0_1250:
	global_load_dword v2, v0, s[34:35] sc1
	s_add_i32 s22, s22, 1
	s_mov_b64 s[42:43], -1
	s_waitcnt vmcnt(0)
	v_lshrrev_b32_e32 v2, 3, v2
	v_cmp_ne_u32_e32 vcc, v2, v1
	s_orn2_b64 s[40:41], vcc, exec
	s_branch .LBB0_1245

.LBB0_1259:
	s_or_b64 exec, exec, s[18:19]
	v_cvt_f32_u32_e32 v3, v0
	s_waitcnt vmcnt(0)
	v_readfirstlane_b32 s16, v2
	s_mov_b64 s[18:19], -1
	v_rcp_iflag_f32_e32 v3, v3
	v_add_u32_e32 v1, s16, v1
	v_add_u32_e32 v4, 1, v1
	v_mul_f32_e32 v2, 0x4f7ffffe, v3
	v_cvt_u32_f32_e32 v2, v2
	v_sub_u32_e32 v3, 0, v0
	v_mul_lo_u32 v3, v3, v2
	v_mul_hi_u32 v3, v2, v3
	v_add_u32_e32 v2, v2, v3
	v_mul_hi_u32 v2, v1, v2
	v_mul_lo_u32 v3, v2, v0
	v_sub_u32_e32 v1, v1, v3
	v_add_u32_e32 v5, 1, v2
	v_cmp_ge_u32_e32 vcc, v1, v0
	v_sub_u32_e32 v3, v1, v0
	s_nop 0
	v_cndmask_b32_e32 v2, v2, v5, vcc
	v_cndmask_b32_e32 v1, v1, v3, vcc
	v_add_u32_e32 v3, 1, v2
	v_cmp_ge_u32_e32 vcc, v1, v0
	s_nop 1
	v_cndmask_b32_e32 v2, v2, v3, vcc
	v_mul_lo_u32 v1, v0, v2
	v_add_u32_e32 v0, v1, v0
	v_cmp_ne_u32_e32 vcc, v4, v0
	v_mov_b64_e32 v[0:1], s[14:15]
	s_and_saveexec_b64 s[16:17], vcc
	s_cbranch_execz .LBB0_1271
	v_mov_b32_e32 v0, 0
	global_load_dword v1, v0, s[34:35] sc1
	s_mov_b64 s[36:37], 0
	s_waitcnt vmcnt(0)
	v_lshrrev_b32_e32 v1, 3, v1
	v_cmp_eq_u32_e32 vcc, v1, v2
	s_and_saveexec_b64 s[18:19], vcc
	s_cbranch_execz .LBB0_1270
	s_mov_b32 s22, 1
	s_branch .LBB0_1263

.LBB0_1267:
	global_load_dword v1, v0, s[34:35] sc1
	s_add_i32 s22, s22, 1
	s_mov_b64 s[40:41], -1
	s_waitcnt vmcnt(0)
	v_lshrrev_b32_e32 v1, 3, v1
	v_cmp_ne_u32_e32 vcc, v1, v2
	s_orn2_b64 s[44:45], vcc, exec
	s_branch .LBB0_1262

.LBB0_1320:
	s_or_b64 exec, exec, s[0:1]
	v_cvt_f32_u32_e32 v4, v2
	s_waitcnt vmcnt(1)
	v_readfirstlane_b32 s0, v3
	v_sub_u32_e32 v3, 0, v2
	v_rcp_iflag_f32_e32 v4, v4
	v_add_u32_e32 v5, s0, v1
	v_mul_f32_e32 v4, 0x4f7ffffe, v4
	v_cvt_u32_f32_e32 v4, v4
	v_mul_lo_u32 v1, v3, v4
	v_mul_hi_u32 v1, v4, v1
	v_add_u32_e32 v1, v4, v1
	v_mul_hi_u32 v1, v5, v1
	v_mul_lo_u32 v3, v1, v2
	v_sub_u32_e32 v3, v5, v3
	v_add_u32_e32 v4, 1, v1
	v_cmp_ge_u32_e32 vcc, v3, v2
	s_nop 1
	v_cndmask_b32_e32 v1, v1, v4, vcc
	v_sub_u32_e32 v4, v3, v2
	v_cndmask_b32_e32 v3, v3, v4, vcc
	v_add_u32_e32 v4, 1, v1
	v_cmp_ge_u32_e32 vcc, v3, v2
	v_add_u32_e32 v3, 1, v5
	s_nop 0
	v_cndmask_b32_e32 v1, v1, v4, vcc
	v_mul_lo_u32 v4, v2, v1
	v_add_u32_e32 v2, v4, v2
	v_cmp_ne_u32_e32 vcc, v3, v2
	s_and_saveexec_b64 s[0:1], vcc
	s_xor_b64 s[0:1], exec, s[0:1]
	s_cbranch_execz .LBB0_1334
	s_waitcnt lgkmcnt(0)
	v_mov_b32_e32 v0, 0
	global_load_dword v2, v0, s[34:35] sc1
	s_waitcnt vmcnt(0)
	v_lshrrev_b32_e32 v2, 3, v2
	v_cmp_eq_u32_e32 vcc, v2, v1
	s_and_saveexec_b64 s[12:13], vcc
	s_cbranch_execz .LBB0_1333
	s_mov_b32 s3, 1
	s_mov_b64 s[16:17], 0
	s_branch .LBB0_1324

.LBB0_1328:
	global_load_dword v2, v0, s[34:35] sc1
	s_add_i32 s3, s3, 1
	s_mov_b64 s[22:23], -1
	s_waitcnt vmcnt(0)
	v_lshrrev_b32_e32 v2, 3, v2
	v_cmp_ne_u32_e32 vcc, v2, v1
	s_orn2_b64 s[20:21], vcc, exec
	s_branch .LBB0_1323

.LBB0_1337:
	s_or_b64 exec, exec, s[12:13]
	v_cvt_f32_u32_e32 v3, v0
	s_waitcnt vmcnt(0)
	v_readfirstlane_b32 s0, v2
	s_mov_b64 s[12:13], -1
	v_rcp_iflag_f32_e32 v3, v3
	v_add_u32_e32 v1, s0, v1
	v_add_u32_e32 v4, 1, v1
	v_mul_f32_e32 v2, 0x4f7ffffe, v3
	v_cvt_u32_f32_e32 v2, v2
	v_sub_u32_e32 v3, 0, v0
	v_mul_lo_u32 v3, v3, v2
	v_mul_hi_u32 v3, v2, v3
	v_add_u32_e32 v2, v2, v3
	v_mul_hi_u32 v2, v1, v2
	v_mul_lo_u32 v3, v2, v0
	v_sub_u32_e32 v1, v1, v3
	v_add_u32_e32 v5, 1, v2
	v_cmp_ge_u32_e32 vcc, v1, v0
	v_sub_u32_e32 v3, v1, v0
	s_nop 0
	v_cndmask_b32_e32 v2, v2, v5, vcc
	v_cndmask_b32_e32 v1, v1, v3, vcc
	v_add_u32_e32 v3, 1, v2
	v_cmp_ge_u32_e32 vcc, v1, v0
	s_nop 1
	v_cndmask_b32_e32 v2, v2, v3, vcc
	v_mul_lo_u32 v1, v0, v2
	v_add_u32_e32 v0, v1, v0
	v_cmp_ne_u32_e32 vcc, v4, v0
	v_mov_b64_e32 v[0:1], s[14:15]
	s_and_saveexec_b64 s[0:1], vcc
	s_cbranch_execz .LBB0_1349
	v_mov_b32_e32 v0, 0
	global_load_dword v1, v0, s[34:35] sc1
	s_mov_b64 s[16:17], 0
	s_waitcnt vmcnt(0)
	v_lshrrev_b32_e32 v1, 3, v1
	v_cmp_eq_u32_e32 vcc, v1, v2
	s_and_saveexec_b64 s[12:13], vcc
	s_cbranch_execz .LBB0_1348
	s_mov_b32 s3, 1
	s_branch .LBB0_1341

.LBB0_1345:
	global_load_dword v1, v0, s[34:35] sc1
	s_add_i32 s3, s3, 1
	s_mov_b64 s[20:21], -1
	s_waitcnt vmcnt(0)
	v_lshrrev_b32_e32 v1, 3, v1
	v_cmp_ne_u32_e32 vcc, v1, v2
	s_orn2_b64 s[24:25], vcc, exec
	s_branch .LBB0_1340
